# in-proj and out-proj K-loops: LDS-DMA loads use SGPR base + 32-bit lane offset (no VALU address adds)
# baseline (speedup 1.0000x reference)
.LBB0_765:
	s_add_u32 s0, s52, 0xfff00080
	s_addc_u32 s54, s53, -1
	s_add_i32 s81, 0, 0x10000
	v_add_u32_e32 v142, s81, v174
	v_add_u32_e32 v172, s14, v174
	ds_read_b128 v[130:133], v142
	ds_read_b128 v[134:137], v142 offset:1024
	ds_read_b128 v[138:141], v142 offset:2048
	ds_read_b128 v[142:145], v142 offset:3072
	ds_read_b128 v[178:181], v172
	ds_read_b128 v[182:185], v172 offset:1024
	ds_read_b128 v[186:189], v172 offset:2048
	ds_read_b128 v[190:193], v172 offset:3072
	s_cmp_eq_u32 s80, 60
	s_cselect_b32 s57, s43, s54
	s_cselect_b32 s56, s49, s0
	s_cselect_b32 s55, s13, s79
	s_cselect_b32 s54, s51, s78
	s_add_i32 m0, s64, 0xc000
	ds_read_b128 v[218:221], v176
	ds_read_b128 v[222:225], v176 offset:1024
	ds_read_b128 v[226:229], v176 offset:2048
	ds_read_b128 v[230:233], v176 offset:3072
	ds_read_b128 v[234:237], v176 offset:4096
	ds_read_b128 v[238:241], v176 offset:5120
	ds_read_b128 v[242:245], v176 offset:6144
	ds_read_b128 v[246:249], v176 offset:7168
	global_load_lds_dwordx4 v168, s[52:53]
	s_add_i32 m0, s64, 0xe000
	s_nop 0
	global_load_lds_dwordx4 v170, s[52:53]
	s_waitcnt vmcnt(8)
	s_waitcnt lgkmcnt(0)
	s_barrier
	s_setprio 1
	s_waitcnt lgkmcnt(0)
	v_mfma_f32_16x16x32_bf16 v[126:129], v[130:133], v[218:221], v[126:129]
	v_mfma_f32_16x16x32_bf16 v[122:125], v[138:141], v[218:221], v[122:125]
	v_mfma_f32_16x16x32_bf16 v[110:113], v[130:133], v[226:229], v[110:113]
	v_mfma_f32_16x16x32_bf16 v[106:109], v[138:141], v[226:229], v[106:109]
	v_mfma_f32_16x16x32_bf16 v[94:97], v[130:133], v[234:237], v[94:97]
	v_mfma_f32_16x16x32_bf16 v[90:93], v[138:141], v[234:237], v[90:93]
	v_mfma_f32_16x16x32_bf16 v[78:81], v[130:133], v[242:245], v[78:81]
	v_mfma_f32_16x16x32_bf16 v[74:77], v[138:141], v[242:245], v[74:77]
	v_mfma_f32_16x16x32_bf16 v[126:129], v[134:137], v[222:225], v[126:129]
	v_mfma_f32_16x16x32_bf16 v[122:125], v[142:145], v[222:225], v[122:125]
	v_mfma_f32_16x16x32_bf16 v[110:113], v[134:137], v[230:233], v[110:113]
	v_mfma_f32_16x16x32_bf16 v[106:109], v[142:145], v[230:233], v[106:109]
	v_mfma_f32_16x16x32_bf16 v[94:97], v[134:137], v[238:241], v[94:97]
	v_mfma_f32_16x16x32_bf16 v[90:93], v[142:145], v[238:241], v[90:93]
	v_mfma_f32_16x16x32_bf16 v[78:81], v[134:137], v[246:249], v[78:81]
	v_mfma_f32_16x16x32_bf16 v[74:77], v[142:145], v[246:249], v[74:77]
	s_setprio 0
	s_setprio 1
	v_mfma_f32_16x16x32_bf16 v[118:121], v[178:181], v[218:221], v[118:121]
	v_mfma_f32_16x16x32_bf16 v[114:117], v[186:189], v[218:221], v[114:117]
	v_mfma_f32_16x16x32_bf16 v[102:105], v[178:181], v[226:229], v[102:105]
	v_mfma_f32_16x16x32_bf16 v[98:101], v[186:189], v[226:229], v[98:101]
	v_mfma_f32_16x16x32_bf16 v[86:89], v[178:181], v[234:237], v[86:89]
	v_mfma_f32_16x16x32_bf16 v[82:85], v[186:189], v[234:237], v[82:85]
	v_mfma_f32_16x16x32_bf16 v[70:73], v[178:181], v[242:245], v[70:73]
	v_mfma_f32_16x16x32_bf16 v[66:69], v[186:189], v[242:245], v[66:69]
	v_mfma_f32_16x16x32_bf16 v[118:121], v[182:185], v[222:225], v[118:121]
	v_mfma_f32_16x16x32_bf16 v[114:117], v[190:193], v[222:225], v[114:117]
	v_mfma_f32_16x16x32_bf16 v[102:105], v[182:185], v[230:233], v[102:105]
	v_mfma_f32_16x16x32_bf16 v[98:101], v[190:193], v[230:233], v[98:101]
	v_mfma_f32_16x16x32_bf16 v[86:89], v[182:185], v[238:241], v[86:89]
	v_mfma_f32_16x16x32_bf16 v[82:85], v[190:193], v[238:241], v[82:85]
	v_mfma_f32_16x16x32_bf16 v[70:73], v[182:185], v[246:249], v[70:73]
	v_mfma_f32_16x16x32_bf16 v[66:69], v[190:193], v[246:249], v[66:69]
	s_setprio 0
	s_barrier
	s_add_i32 s0, s81, s63
	s_mov_b32 m0, s0
	ds_read_b128 v[218:221], v176 offset:16384
	ds_read_b128 v[222:225], v176 offset:17408
	ds_read_b128 v[226:229], v176 offset:18432
	ds_read_b128 v[230:233], v176 offset:19456
	ds_read_b128 v[234:237], v176 offset:20480
	ds_read_b128 v[238:241], v176 offset:21504
	ds_read_b128 v[242:245], v176 offset:22528
	ds_read_b128 v[246:249], v176 offset:23552
	global_load_lds_dwordx4 v194, s[54:55]
	s_add_i32 m0, s0, 0x2000
	s_add_u32 s84, s54, 0x100000
	s_addc_u32 s85, s55, 0
	s_add_i32 s0, s14, s63
	global_load_lds_dwordx4 v150, s[54:55]
	s_mov_b32 m0, s0
	s_nop 0
	global_load_lds_dwordx4 v194, s[84:85]
	s_add_i32 m0, s0, 0x2000
	s_nop 0
	global_load_lds_dwordx4 v150, s[84:85]
	s_mov_b32 m0, s64
	s_nop 0
	global_load_lds_dwordx4 v146, s[56:57]
	s_mov_b32 m0, s65
	s_nop 0
	global_load_lds_dwordx4 v148, s[56:57]
	s_waitcnt vmcnt(8)
	s_waitcnt lgkmcnt(0)
	s_barrier
	s_setprio 1
	s_waitcnt lgkmcnt(0)
	v_mfma_f32_16x16x32_bf16 v[62:65], v[130:133], v[218:221], v[62:65]
	v_mfma_f32_16x16x32_bf16 v[58:61], v[138:141], v[218:221], v[58:61]
	v_mfma_f32_16x16x32_bf16 v[54:57], v[130:133], v[226:229], v[54:57]
	v_mfma_f32_16x16x32_bf16 v[46:49], v[138:141], v[226:229], v[46:49]
	v_mfma_f32_16x16x32_bf16 v[38:41], v[130:133], v[234:237], v[38:41]
	v_mfma_f32_16x16x32_bf16 v[30:33], v[138:141], v[234:237], v[30:33]
	v_mfma_f32_16x16x32_bf16 v[22:25], v[130:133], v[242:245], v[22:25]
	v_mfma_f32_16x16x32_bf16 v[14:17], v[138:141], v[242:245], v[14:17]
	v_mfma_f32_16x16x32_bf16 v[62:65], v[134:137], v[222:225], v[62:65]
	v_mfma_f32_16x16x32_bf16 v[58:61], v[142:145], v[222:225], v[58:61]
	v_mfma_f32_16x16x32_bf16 v[54:57], v[134:137], v[230:233], v[54:57]
	v_mfma_f32_16x16x32_bf16 v[46:49], v[142:145], v[230:233], v[46:49]
	v_mfma_f32_16x16x32_bf16 v[38:41], v[134:137], v[238:241], v[38:41]
	v_mfma_f32_16x16x32_bf16 v[30:33], v[142:145], v[238:241], v[30:33]
	v_mfma_f32_16x16x32_bf16 v[22:25], v[134:137], v[246:249], v[22:25]
	v_mfma_f32_16x16x32_bf16 v[14:17], v[142:145], v[246:249], v[14:17]
	s_setprio 0
	s_setprio 1
	v_mfma_f32_16x16x32_bf16 v[50:53], v[178:181], v[218:221], v[50:53]
	v_mfma_f32_16x16x32_bf16 v[42:45], v[186:189], v[218:221], v[42:45]
	v_mfma_f32_16x16x32_bf16 v[34:37], v[178:181], v[226:229], v[34:37]
	v_mfma_f32_16x16x32_bf16 v[26:29], v[186:189], v[226:229], v[26:29]
	v_mfma_f32_16x16x32_bf16 v[18:21], v[178:181], v[234:237], v[18:21]
	v_mfma_f32_16x16x32_bf16 v[10:13], v[186:189], v[234:237], v[10:13]
	v_mfma_f32_16x16x32_bf16 v[6:9], v[178:181], v[242:245], v[6:9]
	v_mfma_f32_16x16x32_bf16 v[2:5], v[186:189], v[242:245], v[2:5]
	v_mfma_f32_16x16x32_bf16 v[50:53], v[182:185], v[222:225], v[50:53]
	v_mfma_f32_16x16x32_bf16 v[42:45], v[190:193], v[222:225], v[42:45]
	v_mfma_f32_16x16x32_bf16 v[34:37], v[182:185], v[230:233], v[34:37]
	v_mfma_f32_16x16x32_bf16 v[26:29], v[190:193], v[230:233], v[26:29]
	v_mfma_f32_16x16x32_bf16 v[18:21], v[182:185], v[238:241], v[18:21]
	v_mfma_f32_16x16x32_bf16 v[10:13], v[190:193], v[238:241], v[10:13]
	v_mfma_f32_16x16x32_bf16 v[6:9], v[182:185], v[246:249], v[6:9]
	v_mfma_f32_16x16x32_bf16 v[2:5], v[190:193], v[246:249], v[2:5]
	s_setprio 0
	s_barrier
	s_add_i32 s0, 0, 0x18000
	s_add_i32 s81, 0, 0x1c000
	v_add_u32_e32 v142, s0, v174
	v_add_u32_e32 v177, s81, v174
	ds_read_b128 v[130:133], v142
	ds_read_b128 v[134:137], v142 offset:1024
	ds_read_b128 v[138:141], v142 offset:2048
	ds_read_b128 v[142:145], v142 offset:3072
	ds_read_b128 v[178:181], v177
	ds_read_b128 v[182:185], v177 offset:1024
	ds_read_b128 v[186:189], v177 offset:2048
	ds_read_b128 v[190:193], v177 offset:3072
	s_add_u32 s56, s56, 0x100000
	s_addc_u32 s57, s57, 0
	s_mov_b32 m0, s66
	ds_read_b128 v[218:221], v176 offset:32768
	ds_read_b128 v[222:225], v176 offset:33792
	ds_read_b128 v[226:229], v176 offset:34816
	ds_read_b128 v[230:233], v176 offset:35840
	ds_read_b128 v[234:237], v176 offset:36864
	ds_read_b128 v[238:241], v176 offset:37888
	ds_read_b128 v[242:245], v176 offset:38912
	ds_read_b128 v[246:249], v176 offset:39936
	global_load_lds_dwordx4 v146, s[56:57]
	s_mov_b32 m0, s67
	s_nop 0
	global_load_lds_dwordx4 v148, s[56:57]
	s_waitcnt vmcnt(8)
	s_waitcnt lgkmcnt(0)
	s_barrier
	s_setprio 1
	s_waitcnt lgkmcnt(0)
	v_mfma_f32_16x16x32_bf16 v[126:129], v[130:133], v[218:221], v[126:129]
	v_mfma_f32_16x16x32_bf16 v[122:125], v[138:141], v[218:221], v[122:125]
	v_mfma_f32_16x16x32_bf16 v[110:113], v[130:133], v[226:229], v[110:113]
	v_mfma_f32_16x16x32_bf16 v[106:109], v[138:141], v[226:229], v[106:109]
	v_mfma_f32_16x16x32_bf16 v[94:97], v[130:133], v[234:237], v[94:97]
	v_mfma_f32_16x16x32_bf16 v[90:93], v[138:141], v[234:237], v[90:93]
	v_mfma_f32_16x16x32_bf16 v[78:81], v[130:133], v[242:245], v[78:81]
	v_mfma_f32_16x16x32_bf16 v[74:77], v[138:141], v[242:245], v[74:77]
	v_mfma_f32_16x16x32_bf16 v[126:129], v[134:137], v[222:225], v[126:129]
	v_mfma_f32_16x16x32_bf16 v[122:125], v[142:145], v[222:225], v[122:125]
	v_mfma_f32_16x16x32_bf16 v[110:113], v[134:137], v[230:233], v[110:113]
	v_mfma_f32_16x16x32_bf16 v[106:109], v[142:145], v[230:233], v[106:109]
	v_mfma_f32_16x16x32_bf16 v[94:97], v[134:137], v[238:241], v[94:97]
	v_mfma_f32_16x16x32_bf16 v[90:93], v[142:145], v[238:241], v[90:93]
	v_mfma_f32_16x16x32_bf16 v[78:81], v[134:137], v[246:249], v[78:81]
	v_mfma_f32_16x16x32_bf16 v[74:77], v[142:145], v[246:249], v[74:77]
	s_setprio 0
	s_setprio 1
	v_mfma_f32_16x16x32_bf16 v[118:121], v[178:181], v[218:221], v[118:121]
	v_mfma_f32_16x16x32_bf16 v[114:117], v[186:189], v[218:221], v[114:117]
	v_mfma_f32_16x16x32_bf16 v[102:105], v[178:181], v[226:229], v[102:105]
	v_mfma_f32_16x16x32_bf16 v[98:101], v[186:189], v[226:229], v[98:101]
	v_mfma_f32_16x16x32_bf16 v[86:89], v[178:181], v[234:237], v[86:89]
	v_mfma_f32_16x16x32_bf16 v[82:85], v[186:189], v[234:237], v[82:85]
	v_mfma_f32_16x16x32_bf16 v[70:73], v[178:181], v[242:245], v[70:73]
	v_mfma_f32_16x16x32_bf16 v[66:69], v[186:189], v[242:245], v[66:69]
	v_mfma_f32_16x16x32_bf16 v[118:121], v[182:185], v[222:225], v[118:121]
	v_mfma_f32_16x16x32_bf16 v[114:117], v[190:193], v[222:225], v[114:117]
	v_mfma_f32_16x16x32_bf16 v[102:105], v[182:185], v[230:233], v[102:105]
	v_mfma_f32_16x16x32_bf16 v[98:101], v[190:193], v[230:233], v[98:101]
	v_mfma_f32_16x16x32_bf16 v[86:89], v[182:185], v[238:241], v[86:89]
	v_mfma_f32_16x16x32_bf16 v[82:85], v[190:193], v[238:241], v[82:85]
	v_mfma_f32_16x16x32_bf16 v[70:73], v[182:185], v[246:249], v[70:73]
	v_mfma_f32_16x16x32_bf16 v[66:69], v[190:193], v[246:249], v[66:69]
	s_setprio 0
	s_barrier
	s_add_i32 s0, s0, s63
	s_add_u32 s84, s54, 0x80
	s_addc_u32 s85, s55, 0
	s_mov_b32 m0, s0
	ds_read_b128 v[218:221], v176 offset:49152
	ds_read_b128 v[222:225], v176 offset:50176
	ds_read_b128 v[226:229], v176 offset:51200
	ds_read_b128 v[230:233], v176 offset:52224
	ds_read_b128 v[234:237], v176 offset:53248
	ds_read_b128 v[238:241], v176 offset:54272
	ds_read_b128 v[242:245], v176 offset:55296
	ds_read_b128 v[246:249], v176 offset:56320
	global_load_lds_dwordx4 v194, s[84:85]
	s_add_i32 m0, s0, 0x2000
	s_add_u32 s54, s54, 0x100080
	s_addc_u32 s55, s55, 0
	s_add_i32 s0, s81, s63
	global_load_lds_dwordx4 v150, s[84:85]
	s_sub_u32 s84, s56, 0xfff80
	s_subb_u32 s85, s57, 0
	s_mov_b32 m0, s0
	s_nop 0
	global_load_lds_dwordx4 v194, s[54:55]
	s_add_i32 m0, s0, 0x2000
	s_nop 0
	global_load_lds_dwordx4 v150, s[54:55]
	s_mov_b32 m0, s74
	s_nop 0
	global_load_lds_dwordx4 v146, s[84:85]
	s_mov_b32 m0, s75
	s_nop 0
	global_load_lds_dwordx4 v148, s[84:85]
	s_waitcnt vmcnt(8)
	s_waitcnt lgkmcnt(0)
	s_barrier
	s_setprio 1
	s_waitcnt lgkmcnt(0)
	v_mfma_f32_16x16x32_bf16 v[62:65], v[130:133], v[218:221], v[62:65]
	v_mfma_f32_16x16x32_bf16 v[58:61], v[138:141], v[218:221], v[58:61]
	v_mfma_f32_16x16x32_bf16 v[54:57], v[130:133], v[226:229], v[54:57]
	v_mfma_f32_16x16x32_bf16 v[46:49], v[138:141], v[226:229], v[46:49]
	v_mfma_f32_16x16x32_bf16 v[38:41], v[130:133], v[234:237], v[38:41]
	v_mfma_f32_16x16x32_bf16 v[30:33], v[138:141], v[234:237], v[30:33]
	v_mfma_f32_16x16x32_bf16 v[22:25], v[130:133], v[242:245], v[22:25]
	v_mfma_f32_16x16x32_bf16 v[14:17], v[138:141], v[242:245], v[14:17]
	v_mfma_f32_16x16x32_bf16 v[62:65], v[134:137], v[222:225], v[62:65]
	v_mfma_f32_16x16x32_bf16 v[58:61], v[142:145], v[222:225], v[58:61]
	v_mfma_f32_16x16x32_bf16 v[54:57], v[134:137], v[230:233], v[54:57]
	v_mfma_f32_16x16x32_bf16 v[46:49], v[142:145], v[230:233], v[46:49]
	v_mfma_f32_16x16x32_bf16 v[38:41], v[134:137], v[238:241], v[38:41]
	v_mfma_f32_16x16x32_bf16 v[30:33], v[142:145], v[238:241], v[30:33]
	v_mfma_f32_16x16x32_bf16 v[22:25], v[134:137], v[246:249], v[22:25]
	v_mfma_f32_16x16x32_bf16 v[14:17], v[142:145], v[246:249], v[14:17]
	s_setprio 0
	s_setprio 1
	v_mfma_f32_16x16x32_bf16 v[50:53], v[178:181], v[218:221], v[50:53]
	v_mfma_f32_16x16x32_bf16 v[42:45], v[186:189], v[218:221], v[42:45]
	v_mfma_f32_16x16x32_bf16 v[34:37], v[178:181], v[226:229], v[34:37]
	v_mfma_f32_16x16x32_bf16 v[26:29], v[186:189], v[226:229], v[26:29]
	v_mfma_f32_16x16x32_bf16 v[18:21], v[178:181], v[234:237], v[18:21]
	v_mfma_f32_16x16x32_bf16 v[10:13], v[186:189], v[234:237], v[10:13]
	v_mfma_f32_16x16x32_bf16 v[6:9], v[178:181], v[242:245], v[6:9]
	v_mfma_f32_16x16x32_bf16 v[2:5], v[186:189], v[242:245], v[2:5]
	v_mfma_f32_16x16x32_bf16 v[50:53], v[182:185], v[222:225], v[50:53]
	v_mfma_f32_16x16x32_bf16 v[42:45], v[190:193], v[222:225], v[42:45]
	v_mfma_f32_16x16x32_bf16 v[34:37], v[182:185], v[230:233], v[34:37]
	v_mfma_f32_16x16x32_bf16 v[26:29], v[190:193], v[230:233], v[26:29]
	v_mfma_f32_16x16x32_bf16 v[18:21], v[182:185], v[238:241], v[18:21]
	v_mfma_f32_16x16x32_bf16 v[10:13], v[190:193], v[238:241], v[10:13]
	v_mfma_f32_16x16x32_bf16 v[6:9], v[182:185], v[246:249], v[6:9]
	v_mfma_f32_16x16x32_bf16 v[2:5], v[190:193], v[246:249], v[2:5]
	s_setprio 0
	s_barrier
	s_add_i32 s80, s80, 2
	s_add_u32 s52, s52, 0x100
	s_addc_u32 s53, s53, 0
	s_add_u32 s78, s78, 0x100
	s_addc_u32 s79, s79, 0
	s_cmp_gt_u32 s80, 61
	s_cbranch_scc0 .LBB0_765
	s_and_b64 vcc, exec, s[10:11]
	s_cbranch_vccz .LBB0_768
	s_barrier
